# code placement: the six main GEMM K-loop heads (phase C, the four gm units, phase F) padded to 64-byte boundaries, everything else at its previous placement; on top of v64
# speedup vs baseline: 1.0043x; 1.0010x over previous
.LBB0_184:
	s_ashr_i32 s11, s10, 31
	s_lshl_b64 s[14:15], s[10:11], 20
	v_readlane_b32 s16, v252, 6
	v_readlane_b32 s17, v252, 7
	s_add_u32 s14, s16, s14
	s_addc_u32 s15, s17, s15
	s_and_b64 s[16:17], s[0:1], exec
	s_cselect_b32 s11, s15, s19
	s_cselect_b32 s37, s14, s18
	s_ashr_i32 s13, s12, 31
	s_lshl_b64 s[16:17], s[12:13], 20
	s_add_u32 s16, s52, s16
	s_addc_u32 s17, s53, s17
	s_and_b64 s[22:23], s[0:1], exec
	s_cselect_b32 s13, s17, s21
	s_cselect_b32 s38, s16, s20
	s_add_u32 s18, s18, 0x80080
	s_addc_u32 s19, s19, 0
	s_add_u32 s39, s20, 0x100
	v_mov_b32_e32 v0, 0
	s_addc_u32 s40, s21, 0
	s_mov_b32 s41, -2
	v_mov_b32_e32 v1, v0
	v_mov_b32_e32 v2, v0
	v_mov_b32_e32 v3, v0
	v_mov_b32_e32 v4, v0
	v_mov_b32_e32 v5, v0
	v_mov_b32_e32 v6, v0
	v_mov_b32_e32 v7, v0
	v_mov_b32_e32 v8, v0
	v_mov_b32_e32 v9, v0
	v_mov_b32_e32 v10, v0
	v_mov_b32_e32 v11, v0
	v_mov_b32_e32 v12, v0
	v_mov_b32_e32 v13, v0
	v_mov_b32_e32 v14, v0
	v_mov_b32_e32 v15, v0
	v_mov_b32_e32 v24, v0
	v_mov_b32_e32 v25, v0
	v_mov_b32_e32 v26, v0
	v_mov_b32_e32 v27, v0
	v_mov_b32_e32 v28, v0
	v_mov_b32_e32 v29, v0
	v_mov_b32_e32 v30, v0
	v_mov_b32_e32 v31, v0
	v_mov_b32_e32 v40, v0
	v_mov_b32_e32 v41, v0
	v_mov_b32_e32 v42, v0
	v_mov_b32_e32 v43, v0
	v_mov_b32_e32 v44, v0
	v_mov_b32_e32 v45, v0
	v_mov_b32_e32 v46, v0
	v_mov_b32_e32 v47, v0
	v_mov_b32_e32 v16, v0
	v_mov_b32_e32 v17, v0
	v_mov_b32_e32 v18, v0
	v_mov_b32_e32 v19, v0
	v_mov_b32_e32 v20, v0
	v_mov_b32_e32 v21, v0
	v_mov_b32_e32 v22, v0
	v_mov_b32_e32 v23, v0
	v_mov_b32_e32 v32, v0
	v_mov_b32_e32 v33, v0
	v_mov_b32_e32 v34, v0
	v_mov_b32_e32 v35, v0
	v_mov_b32_e32 v36, v0
	v_mov_b32_e32 v37, v0
	v_mov_b32_e32 v38, v0
	v_mov_b32_e32 v39, v0
	v_mov_b32_e32 v48, v0
	v_mov_b32_e32 v49, v0
	v_mov_b32_e32 v50, v0
	v_mov_b32_e32 v51, v0
	v_mov_b32_e32 v52, v0
	v_mov_b32_e32 v53, v0
	v_mov_b32_e32 v54, v0
	v_mov_b32_e32 v55, v0
	v_mov_b32_e32 v56, v0
	v_mov_b32_e32 v57, v0
	v_mov_b32_e32 v58, v0
	v_mov_b32_e32 v59, v0
	v_mov_b32_e32 v60, v0
	v_mov_b32_e32 v61, v0
	v_mov_b32_e32 v62, v0
	v_mov_b32_e32 v63, v0
	v_mov_b32_e32 v64, v0
	v_mov_b32_e32 v65, v0
	v_mov_b32_e32 v66, v0
	v_mov_b32_e32 v67, v0
	v_mov_b32_e32 v68, v0
	v_mov_b32_e32 v69, v0
	v_mov_b32_e32 v70, v0
	v_mov_b32_e32 v71, v0
	v_mov_b32_e32 v72, v0
	v_mov_b32_e32 v73, v0
	v_mov_b32_e32 v74, v0
	v_mov_b32_e32 v75, v0
	v_mov_b32_e32 v76, v0
	v_mov_b32_e32 v77, v0
	v_mov_b32_e32 v78, v0
	v_mov_b32_e32 v79, v0
	v_mov_b32_e32 v88, v0
	v_mov_b32_e32 v89, v0
	v_mov_b32_e32 v90, v0
	v_mov_b32_e32 v91, v0
	v_mov_b32_e32 v92, v0
	v_mov_b32_e32 v93, v0
	v_mov_b32_e32 v94, v0
	v_mov_b32_e32 v95, v0
	v_mov_b32_e32 v104, v0
	v_mov_b32_e32 v105, v0
	v_mov_b32_e32 v106, v0
	v_mov_b32_e32 v107, v0
	v_mov_b32_e32 v108, v0
	v_mov_b32_e32 v109, v0
	v_mov_b32_e32 v110, v0
	v_mov_b32_e32 v111, v0
	v_mov_b32_e32 v80, v0
	v_mov_b32_e32 v81, v0
	v_mov_b32_e32 v82, v0
	v_mov_b32_e32 v83, v0
	v_mov_b32_e32 v84, v0
	v_mov_b32_e32 v85, v0
	v_mov_b32_e32 v86, v0
	v_mov_b32_e32 v87, v0
	v_mov_b32_e32 v96, v0
	v_mov_b32_e32 v97, v0
	v_mov_b32_e32 v98, v0
	v_mov_b32_e32 v99, v0
	v_mov_b32_e32 v100, v0
	v_mov_b32_e32 v101, v0
	v_mov_b32_e32 v102, v0
	v_mov_b32_e32 v103, v0
	v_mov_b32_e32 v112, v0
	v_mov_b32_e32 v113, v0
	v_mov_b32_e32 v114, v0
	v_mov_b32_e32 v115, v0
	v_mov_b32_e32 v116, v0
	v_mov_b32_e32 v117, v0
	v_mov_b32_e32 v118, v0
	v_mov_b32_e32 v119, v0
	v_mov_b32_e32 v120, v0
	v_mov_b32_e32 v121, v0
	v_mov_b32_e32 v122, v0
	v_mov_b32_e32 v123, v0
	v_mov_b32_e32 v124, v0
	v_mov_b32_e32 v125, v0
	v_mov_b32_e32 v126, v0
	v_mov_b32_e32 v127, v0
	s_nop 0
	s_nop 0
	s_nop 0

.LBB0_243:
	s_or_b64 exec, exec, s[8:9]
	s_waitcnt vmcnt(0)
	s_branch .Lpadskip_4
	s_nop 0
	s_nop 0
	s_nop 0
	s_nop 0
	s_nop 0
	s_nop 0
	s_nop 0
	s_nop 0
	s_nop 0
	s_nop 0
	s_nop 0
	s_nop 0
	s_nop 0
	s_nop 0
	s_nop 0
	s_nop 0
	s_nop 0
	s_nop 0
	s_nop 0
	s_nop 0
	s_nop 0
	s_nop 0
	s_nop 0
	s_nop 0
	s_nop 0
	s_nop 0
	s_nop 0
	s_nop 0
	s_nop 0
	s_nop 0
	s_nop 0
	s_nop 0
	s_nop 0
	s_nop 0
	s_nop 0
	s_nop 0
	s_nop 0
	s_nop 0
	s_nop 0
	s_nop 0
	s_nop 0
	s_nop 0
	s_nop 0
	s_nop 0
	s_nop 0
	s_nop 0
	s_nop 0
	s_nop 0
	s_nop 0
	s_nop 0
	s_nop 0
	s_nop 0
	s_nop 0
	s_nop 0
	s_nop 0
	s_nop 0
	s_nop 0
	s_nop 0
	s_nop 0
	s_nop 0

.LBB0_754:
	s_mov_b32 s12, s3
	s_lshl_b64 s[30:31], s[12:13], 20
	v_readlane_b32 s0, v252, 6
	s_mov_b32 s87, s3
	v_readlane_b32 s1, v252, 7
	s_add_u32 s3, s0, s30
	s_mov_b32 s24, s2
	s_mov_b32 s25, s13
	s_addc_u32 s10, s1, s31
	s_lshl_b64 s[34:35], s[24:25], 20
	s_add_u32 s0, s40, s34
	s_addc_u32 s1, s41, s35
	s_mov_b32 s86, s2
	s_add_u32 s2, s0, 0x800000
	s_addc_u32 s11, s1, 0
	s_add_u32 s28, s58, s38
	s_addc_u32 s29, s59, s39
	s_add_u32 s33, s72, s36
	v_mov_b32_e32 v0, 0
	v_lshl_add_u64 v[128:129], v[142:143], 0, s[38:39]
	v_lshl_add_u64 v[130:131], v[144:145], 0, s[38:39]
	s_addc_u32 s36, s73, s37
	s_mov_b32 s37, -2
	s_mov_b64 s[0:1], 0
	v_mov_b32_e32 v1, v0
	v_mov_b32_e32 v2, v0
	v_mov_b32_e32 v3, v0
	v_mov_b32_e32 v4, v0
	v_mov_b32_e32 v5, v0
	v_mov_b32_e32 v6, v0
	v_mov_b32_e32 v7, v0
	v_mov_b32_e32 v16, v0
	v_mov_b32_e32 v17, v0
	v_mov_b32_e32 v18, v0
	v_mov_b32_e32 v19, v0
	v_mov_b32_e32 v20, v0
	v_mov_b32_e32 v21, v0
	v_mov_b32_e32 v22, v0
	v_mov_b32_e32 v23, v0
	v_mov_b32_e32 v32, v0
	v_mov_b32_e32 v33, v0
	v_mov_b32_e32 v34, v0
	v_mov_b32_e32 v35, v0
	v_mov_b32_e32 v36, v0
	v_mov_b32_e32 v37, v0
	v_mov_b32_e32 v38, v0
	v_mov_b32_e32 v39, v0
	v_mov_b32_e32 v48, v0
	v_mov_b32_e32 v49, v0
	v_mov_b32_e32 v50, v0
	v_mov_b32_e32 v51, v0
	v_mov_b32_e32 v52, v0
	v_mov_b32_e32 v53, v0
	v_mov_b32_e32 v54, v0
	v_mov_b32_e32 v55, v0
	v_mov_b32_e32 v8, v0
	v_mov_b32_e32 v9, v0
	v_mov_b32_e32 v10, v0
	v_mov_b32_e32 v11, v0
	v_mov_b32_e32 v12, v0
	v_mov_b32_e32 v13, v0
	v_mov_b32_e32 v14, v0
	v_mov_b32_e32 v15, v0
	v_mov_b32_e32 v24, v0
	v_mov_b32_e32 v25, v0
	v_mov_b32_e32 v26, v0
	v_mov_b32_e32 v27, v0
	v_mov_b32_e32 v28, v0
	v_mov_b32_e32 v29, v0
	v_mov_b32_e32 v30, v0
	v_mov_b32_e32 v31, v0
	v_mov_b32_e32 v40, v0
	v_mov_b32_e32 v41, v0
	v_mov_b32_e32 v42, v0
	v_mov_b32_e32 v43, v0
	v_mov_b32_e32 v44, v0
	v_mov_b32_e32 v45, v0
	v_mov_b32_e32 v46, v0
	v_mov_b32_e32 v47, v0
	v_mov_b32_e32 v56, v0
	v_mov_b32_e32 v57, v0
	v_mov_b32_e32 v58, v0
	v_mov_b32_e32 v59, v0
	v_mov_b32_e32 v60, v0
	v_mov_b32_e32 v61, v0
	v_mov_b32_e32 v62, v0
	v_mov_b32_e32 v63, v0
	v_mov_b32_e32 v64, v0
	v_mov_b32_e32 v65, v0
	v_mov_b32_e32 v66, v0
	v_mov_b32_e32 v67, v0
	v_mov_b32_e32 v68, v0
	v_mov_b32_e32 v69, v0
	v_mov_b32_e32 v70, v0
	v_mov_b32_e32 v71, v0
	v_mov_b32_e32 v80, v0
	v_mov_b32_e32 v81, v0
	v_mov_b32_e32 v82, v0
	v_mov_b32_e32 v83, v0
	v_mov_b32_e32 v84, v0
	v_mov_b32_e32 v85, v0
	v_mov_b32_e32 v86, v0
	v_mov_b32_e32 v87, v0
	v_mov_b32_e32 v96, v0
	v_mov_b32_e32 v97, v0
	v_mov_b32_e32 v98, v0
	v_mov_b32_e32 v99, v0
	v_mov_b32_e32 v100, v0
	v_mov_b32_e32 v101, v0
	v_mov_b32_e32 v102, v0
	v_mov_b32_e32 v103, v0
	v_mov_b32_e32 v112, v0
	v_mov_b32_e32 v113, v0
	v_mov_b32_e32 v114, v0
	v_mov_b32_e32 v115, v0
	v_mov_b32_e32 v116, v0
	v_mov_b32_e32 v117, v0
	v_mov_b32_e32 v118, v0
	v_mov_b32_e32 v119, v0
	v_mov_b32_e32 v72, v0
	v_mov_b32_e32 v73, v0
	v_mov_b32_e32 v74, v0
	v_mov_b32_e32 v75, v0
	v_mov_b32_e32 v76, v0
	v_mov_b32_e32 v77, v0
	v_mov_b32_e32 v78, v0
	v_mov_b32_e32 v79, v0
	v_mov_b32_e32 v88, v0
	v_mov_b32_e32 v89, v0
	v_mov_b32_e32 v90, v0
	v_mov_b32_e32 v91, v0
	v_mov_b32_e32 v92, v0
	v_mov_b32_e32 v93, v0
	v_mov_b32_e32 v94, v0
	v_mov_b32_e32 v95, v0
	v_mov_b32_e32 v104, v0
	v_mov_b32_e32 v105, v0
	v_mov_b32_e32 v106, v0
	v_mov_b32_e32 v107, v0
	v_mov_b32_e32 v108, v0
	v_mov_b32_e32 v109, v0
	v_mov_b32_e32 v110, v0
	v_mov_b32_e32 v111, v0
	v_mov_b32_e32 v120, v0
	v_mov_b32_e32 v121, v0
	v_mov_b32_e32 v122, v0
	v_mov_b32_e32 v123, v0
	v_mov_b32_e32 v124, v0
	v_mov_b32_e32 v125, v0
	v_mov_b32_e32 v126, v0
	v_mov_b32_e32 v127, v0
	s_nop 0
	s_nop 0
	s_nop 0
	s_nop 0
	s_nop 0
	s_nop 0
	s_nop 0
	s_nop 0
	s_nop 0

.LBB0_760:
	s_lshl_b64 s[26:27], s[12:13], 19
	s_add_u32 s2, s6, s26
	s_addc_u32 s3, s7, s27
	s_lshl_b64 s[28:29], s[24:25], 19
	s_add_u32 s10, s66, s28
	s_addc_u32 s11, s67, s29
	s_add_u32 s25, s58, s30
	s_addc_u32 s33, s59, s31
	s_add_u32 s37, s74, s34
	v_mov_b32_e32 v0, 0
	v_lshl_add_u64 v[128:129], v[142:143], 0, s[30:31]
	v_lshl_add_u64 v[130:131], v[144:145], 0, s[30:31]
	s_addc_u32 s38, s75, s35
	s_mov_b32 s39, -2
	s_mov_b64 s[30:31], 0
	v_mov_b32_e32 v1, v0
	v_mov_b32_e32 v2, v0
	v_mov_b32_e32 v3, v0
	v_mov_b32_e32 v4, v0
	v_mov_b32_e32 v5, v0
	v_mov_b32_e32 v6, v0
	v_mov_b32_e32 v7, v0
	v_mov_b32_e32 v16, v0
	v_mov_b32_e32 v17, v0
	v_mov_b32_e32 v18, v0
	v_mov_b32_e32 v19, v0
	v_mov_b32_e32 v20, v0
	v_mov_b32_e32 v21, v0
	v_mov_b32_e32 v22, v0
	v_mov_b32_e32 v23, v0
	v_mov_b32_e32 v32, v0
	v_mov_b32_e32 v33, v0
	v_mov_b32_e32 v34, v0
	v_mov_b32_e32 v35, v0
	v_mov_b32_e32 v36, v0
	v_mov_b32_e32 v37, v0
	v_mov_b32_e32 v38, v0
	v_mov_b32_e32 v39, v0
	v_mov_b32_e32 v48, v0
	v_mov_b32_e32 v49, v0
	v_mov_b32_e32 v50, v0
	v_mov_b32_e32 v51, v0
	v_mov_b32_e32 v52, v0
	v_mov_b32_e32 v53, v0
	v_mov_b32_e32 v54, v0
	v_mov_b32_e32 v55, v0
	v_mov_b32_e32 v8, v0
	v_mov_b32_e32 v9, v0
	v_mov_b32_e32 v10, v0
	v_mov_b32_e32 v11, v0
	v_mov_b32_e32 v12, v0
	v_mov_b32_e32 v13, v0
	v_mov_b32_e32 v14, v0
	v_mov_b32_e32 v15, v0
	v_mov_b32_e32 v24, v0
	v_mov_b32_e32 v25, v0
	v_mov_b32_e32 v26, v0
	v_mov_b32_e32 v27, v0
	v_mov_b32_e32 v28, v0
	v_mov_b32_e32 v29, v0
	v_mov_b32_e32 v30, v0
	v_mov_b32_e32 v31, v0
	v_mov_b32_e32 v40, v0
	v_mov_b32_e32 v41, v0
	v_mov_b32_e32 v42, v0
	v_mov_b32_e32 v43, v0
	v_mov_b32_e32 v44, v0
	v_mov_b32_e32 v45, v0
	v_mov_b32_e32 v46, v0
	v_mov_b32_e32 v47, v0
	v_mov_b32_e32 v56, v0
	v_mov_b32_e32 v57, v0
	v_mov_b32_e32 v58, v0
	v_mov_b32_e32 v59, v0
	v_mov_b32_e32 v60, v0
	v_mov_b32_e32 v61, v0
	v_mov_b32_e32 v62, v0
	v_mov_b32_e32 v63, v0
	v_mov_b32_e32 v64, v0
	v_mov_b32_e32 v65, v0
	v_mov_b32_e32 v66, v0
	v_mov_b32_e32 v67, v0
	v_mov_b32_e32 v68, v0
	v_mov_b32_e32 v69, v0
	v_mov_b32_e32 v70, v0
	v_mov_b32_e32 v71, v0
	v_mov_b32_e32 v80, v0
	v_mov_b32_e32 v81, v0
	v_mov_b32_e32 v82, v0
	v_mov_b32_e32 v83, v0
	v_mov_b32_e32 v84, v0
	v_mov_b32_e32 v85, v0
	v_mov_b32_e32 v86, v0
	v_mov_b32_e32 v87, v0
	v_mov_b32_e32 v96, v0
	v_mov_b32_e32 v97, v0
	v_mov_b32_e32 v98, v0
	v_mov_b32_e32 v99, v0
	v_mov_b32_e32 v100, v0
	v_mov_b32_e32 v101, v0
	v_mov_b32_e32 v102, v0
	v_mov_b32_e32 v103, v0
	v_mov_b32_e32 v112, v0
	v_mov_b32_e32 v113, v0
	v_mov_b32_e32 v114, v0
	v_mov_b32_e32 v115, v0
	v_mov_b32_e32 v116, v0
	v_mov_b32_e32 v117, v0
	v_mov_b32_e32 v118, v0
	v_mov_b32_e32 v119, v0
	v_mov_b32_e32 v72, v0
	v_mov_b32_e32 v73, v0
	v_mov_b32_e32 v74, v0
	v_mov_b32_e32 v75, v0
	v_mov_b32_e32 v76, v0
	v_mov_b32_e32 v77, v0
	v_mov_b32_e32 v78, v0
	v_mov_b32_e32 v79, v0
	v_mov_b32_e32 v88, v0
	v_mov_b32_e32 v89, v0
	v_mov_b32_e32 v90, v0
	v_mov_b32_e32 v91, v0
	v_mov_b32_e32 v92, v0
	v_mov_b32_e32 v93, v0
	v_mov_b32_e32 v94, v0
	v_mov_b32_e32 v95, v0
	v_mov_b32_e32 v104, v0
	v_mov_b32_e32 v105, v0
	v_mov_b32_e32 v106, v0
	v_mov_b32_e32 v107, v0
	v_mov_b32_e32 v108, v0
	v_mov_b32_e32 v109, v0
	v_mov_b32_e32 v110, v0
	v_mov_b32_e32 v111, v0
	v_mov_b32_e32 v120, v0
	v_mov_b32_e32 v121, v0
	v_mov_b32_e32 v122, v0
	v_mov_b32_e32 v123, v0
	v_mov_b32_e32 v124, v0
	v_mov_b32_e32 v125, v0
	v_mov_b32_e32 v126, v0
	v_mov_b32_e32 v127, v0
	s_nop 0
	s_nop 0
	s_nop 0
	s_nop 0
	s_nop 0
	s_nop 0
	s_nop 0

.LBB0_766:
	s_add_u32 s43, s64, s26
	s_addc_u32 s33, s65, s27
	s_add_u32 s11, s68, s28
	s_addc_u32 s42, s69, s29
	s_add_u32 s25, s58, s26
	s_addc_u32 s10, s59, s27
	s_add_u32 s2, s76, s28
	v_mov_b32_e32 v0, 0
	v_lshl_add_u64 v[128:129], v[146:147], 0, s[26:27]
	v_lshl_add_u64 v[130:131], v[148:149], 0, s[26:27]
	s_addc_u32 s3, s77, s29
	s_mov_b32 s48, -2
	s_mov_b64 s[34:35], 0
	v_mov_b32_e32 v1, v0
	v_mov_b32_e32 v2, v0
	v_mov_b32_e32 v3, v0
	v_mov_b32_e32 v4, v0
	v_mov_b32_e32 v5, v0
	v_mov_b32_e32 v6, v0
	v_mov_b32_e32 v7, v0
	v_mov_b32_e32 v24, v0
	v_mov_b32_e32 v25, v0
	v_mov_b32_e32 v26, v0
	v_mov_b32_e32 v27, v0
	v_mov_b32_e32 v36, v0
	v_mov_b32_e32 v37, v0
	v_mov_b32_e32 v38, v0
	v_mov_b32_e32 v39, v0
	v_mov_b32_e32 v72, v0
	v_mov_b32_e32 v73, v0
	v_mov_b32_e32 v74, v0
	v_mov_b32_e32 v75, v0
	v_mov_b32_e32 v76, v0
	v_mov_b32_e32 v77, v0
	v_mov_b32_e32 v78, v0
	v_mov_b32_e32 v79, v0
	v_mov_b32_e32 v96, v0
	v_mov_b32_e32 v97, v0
	v_mov_b32_e32 v98, v0
	v_mov_b32_e32 v99, v0
	v_mov_b32_e32 v116, v0
	v_mov_b32_e32 v117, v0
	v_mov_b32_e32 v118, v0
	v_mov_b32_e32 v119, v0
	v_mov_b32_e32 v16, v0
	v_mov_b32_e32 v17, v0
	v_mov_b32_e32 v18, v0
	v_mov_b32_e32 v19, v0
	v_mov_b32_e32 v20, v0
	v_mov_b32_e32 v21, v0
	v_mov_b32_e32 v22, v0
	v_mov_b32_e32 v23, v0
	v_mov_b32_e32 v56, v0
	v_mov_b32_e32 v57, v0
	v_mov_b32_e32 v58, v0
	v_mov_b32_e32 v59, v0
	v_mov_b32_e32 v60, v0
	v_mov_b32_e32 v61, v0
	v_mov_b32_e32 v62, v0
	v_mov_b32_e32 v63, v0
	v_mov_b32_e32 v88, v0
	v_mov_b32_e32 v89, v0
	v_mov_b32_e32 v90, v0
	v_mov_b32_e32 v91, v0
	v_mov_b32_e32 v92, v0
	v_mov_b32_e32 v93, v0
	v_mov_b32_e32 v94, v0
	v_mov_b32_e32 v95, v0
	v_mov_b32_e32 v120, v0
	v_mov_b32_e32 v121, v0
	v_mov_b32_e32 v122, v0
	v_mov_b32_e32 v123, v0
	v_mov_b32_e32 v124, v0
	v_mov_b32_e32 v125, v0
	v_mov_b32_e32 v126, v0
	v_mov_b32_e32 v127, v0
	v_mov_b32_e32 v112, v0
	v_mov_b32_e32 v113, v0
	v_mov_b32_e32 v114, v0
	v_mov_b32_e32 v115, v0
	v_mov_b32_e32 v108, v0
	v_mov_b32_e32 v109, v0
	v_mov_b32_e32 v110, v0
	v_mov_b32_e32 v111, v0
	v_mov_b32_e32 v84, v0
	v_mov_b32_e32 v85, v0
	v_mov_b32_e32 v86, v0
	v_mov_b32_e32 v87, v0
	v_mov_b32_e32 v80, v0
	v_mov_b32_e32 v81, v0
	v_mov_b32_e32 v82, v0
	v_mov_b32_e32 v83, v0
	v_mov_b32_e32 v52, v0
	v_mov_b32_e32 v53, v0
	v_mov_b32_e32 v54, v0
	v_mov_b32_e32 v55, v0
	v_mov_b32_e32 v48, v0
	v_mov_b32_e32 v49, v0
	v_mov_b32_e32 v50, v0
	v_mov_b32_e32 v51, v0
	v_mov_b32_e32 v32, v0
	v_mov_b32_e32 v33, v0
	v_mov_b32_e32 v34, v0
	v_mov_b32_e32 v35, v0
	v_mov_b32_e32 v28, v0
	v_mov_b32_e32 v29, v0
	v_mov_b32_e32 v30, v0
	v_mov_b32_e32 v31, v0
	v_mov_b32_e32 v104, v0
	v_mov_b32_e32 v105, v0
	v_mov_b32_e32 v106, v0
	v_mov_b32_e32 v107, v0
	v_mov_b32_e32 v100, v0
	v_mov_b32_e32 v101, v0
	v_mov_b32_e32 v102, v0
	v_mov_b32_e32 v103, v0
	v_mov_b32_e32 v68, v0
	v_mov_b32_e32 v69, v0
	v_mov_b32_e32 v70, v0
	v_mov_b32_e32 v71, v0
	v_mov_b32_e32 v64, v0
	v_mov_b32_e32 v65, v0
	v_mov_b32_e32 v66, v0
	v_mov_b32_e32 v67, v0
	v_mov_b32_e32 v44, v0
	v_mov_b32_e32 v45, v0
	v_mov_b32_e32 v46, v0
	v_mov_b32_e32 v47, v0
	v_mov_b32_e32 v40, v0
	v_mov_b32_e32 v41, v0
	v_mov_b32_e32 v42, v0
	v_mov_b32_e32 v43, v0
	v_mov_b32_e32 v12, v0
	v_mov_b32_e32 v13, v0
	v_mov_b32_e32 v14, v0
	v_mov_b32_e32 v15, v0
	v_mov_b32_e32 v8, v0
	v_mov_b32_e32 v9, v0
	v_mov_b32_e32 v10, v0
	v_mov_b32_e32 v11, v0
	s_nop 0
	s_nop 0
	s_nop 0
	s_nop 0
	s_nop 0

.Lpadskip_2:
.LBB0_772:
	s_add_i32 s85, s85, 1
	v_readlane_b32 s2, v252, 26
	s_mul_hi_u32 s3, s85, s2
	s_mul_i32 s2, s85, s2
	v_readlane_b32 s4, v252, 0
	s_add_u32 s2, s2, s4
	s_addc_u32 s3, s3, 0
	v_cmp_lt_u64_e64 s[4:5], s[2:3], v[154:155]
	s_lshl_b32 s3, s2, 3
	s_and_b32 s3, s3, 56
	s_bfe_u32 s34, s2, 0x30003
	s_or_b32 s3, s34, s3
	s_lshr_b32 s2, s2, 6
	s_and_b64 s[34:35], s[4:5], exec
	s_cselect_b32 s34, s3, s87
	s_cselect_b32 s36, s2, s86
	s_ashr_i32 s35, s34, 31
	s_lshl_b64 s[38:39], s[34:35], 20
	v_readlane_b32 s34, v252, 6
	v_readlane_b32 s35, v252, 7
	s_add_u32 s37, s34, s38
	s_addc_u32 s48, s35, s39
	s_and_b64 s[34:35], s[4:5], exec
	s_cselect_b32 s33, s48, s33
	s_cselect_b32 s43, s37, s43
	s_ashr_i32 s37, s36, 31
	s_lshl_b64 s[36:37], s[36:37], 20
	s_add_u32 s48, s40, s36
	s_addc_u32 s49, s41, s37
	s_and_b64 s[34:35], s[4:5], exec
	s_cselect_b32 s42, s49, s42
	s_cselect_b32 s11, s48, s11
	s_add_u32 s48, s78, s28
	v_lshl_add_u64 v[128:129], v[150:151], 0, s[26:27]
	v_lshl_add_u64 v[130:131], v[152:153], 0, s[26:27]
	s_addc_u32 s49, s79, s29
	s_mov_b32 s86, -2
	s_mov_b64 s[26:27], 0
	s_nop 0
	s_nop 0
	s_nop 0

.LBB0_838:
	s_add_i32 s39, s39, 1
	s_mov_b64 s[28:29], s[4:5]
	s_mul_i32 s1, s39, s96
	v_readlane_b32 s4, v252, 0
	s_mul_hi_u32 s0, s39, s96
	s_add_u32 s4, s1, s4
	s_addc_u32 s5, s0, 0
	v_cmp_lt_u64_e64 s[0:1], s[4:5], v[138:139]
	s_lshl_b32 s5, s4, 3
	s_and_b32 s5, s5, 56
	s_bfe_u32 s30, s4, 0x30003
	s_mov_b64 s[26:27], s[12:13]
	s_mov_b32 s47, s62
	s_mov_b32 s48, s63
	s_mov_b32 s12, s63
	s_mov_b32 s13, s62
	s_or_b32 s62, s30, s5
	s_lshr_b32 s63, s4, 6
	s_and_b64 s[4:5], s[0:1], exec
	s_cselect_b32 s4, s62, s13
	s_cselect_b32 s30, s63, s12
	s_ashr_i32 s5, s4, 31
	s_lshl_b64 s[4:5], s[4:5], 20
	s_add_u32 s12, s8, s4
	s_addc_u32 s13, s9, s5
	s_and_b64 s[4:5], s[0:1], exec
	s_cselect_b32 s49, s13, s27
	s_cselect_b32 s50, s12, s26
	s_ashr_i32 s31, s30, 31
	s_lshl_b64 s[4:5], s[30:31], 20
	s_add_u32 s4, s2, s4
	s_addc_u32 s5, s33, s5
	s_and_b64 s[30:31], s[0:1], exec
	s_cselect_b32 s51, s5, s29
	s_cselect_b32 s52, s4, s28
	s_add_u32 s26, s26, 0x80080
	s_addc_u32 s27, s27, 0
	s_add_u32 s53, s28, 0x100
	v_mov_b32_e32 v0, 0
	s_addc_u32 s64, s29, 0
	s_mov_b32 s65, -2
	v_mov_b32_e32 v1, v0
	v_mov_b32_e32 v2, v0
	v_mov_b32_e32 v3, v0
	v_mov_b32_e32 v4, v0
	v_mov_b32_e32 v5, v0
	v_mov_b32_e32 v6, v0
	v_mov_b32_e32 v7, v0
	v_mov_b32_e32 v8, v0
	v_mov_b32_e32 v9, v0
	v_mov_b32_e32 v10, v0
	v_mov_b32_e32 v11, v0
	v_mov_b32_e32 v12, v0
	v_mov_b32_e32 v13, v0
	v_mov_b32_e32 v14, v0
	v_mov_b32_e32 v15, v0
	v_mov_b32_e32 v16, v0
	v_mov_b32_e32 v17, v0
	v_mov_b32_e32 v18, v0
	v_mov_b32_e32 v19, v0
	v_mov_b32_e32 v20, v0
	v_mov_b32_e32 v21, v0
	v_mov_b32_e32 v22, v0
	v_mov_b32_e32 v23, v0
	v_mov_b32_e32 v24, v0
	v_mov_b32_e32 v25, v0
	v_mov_b32_e32 v26, v0
	v_mov_b32_e32 v27, v0
	v_mov_b32_e32 v28, v0
	v_mov_b32_e32 v29, v0
	v_mov_b32_e32 v30, v0
	v_mov_b32_e32 v31, v0
	v_mov_b32_e32 v52, v0
	v_mov_b32_e32 v53, v0
	v_mov_b32_e32 v54, v0
	v_mov_b32_e32 v55, v0
	v_mov_b32_e32 v60, v0
	v_mov_b32_e32 v61, v0
	v_mov_b32_e32 v62, v0
	v_mov_b32_e32 v63, v0
	v_mov_b32_e32 v72, v0
	v_mov_b32_e32 v73, v0
	v_mov_b32_e32 v74, v0
	v_mov_b32_e32 v75, v0
	v_mov_b32_e32 v76, v0
	v_mov_b32_e32 v77, v0
	v_mov_b32_e32 v78, v0
	v_mov_b32_e32 v79, v0
	v_mov_b32_e32 v80, v0
	v_mov_b32_e32 v81, v0
	v_mov_b32_e32 v82, v0
	v_mov_b32_e32 v83, v0
	v_mov_b32_e32 v84, v0
	v_mov_b32_e32 v85, v0
	v_mov_b32_e32 v86, v0
	v_mov_b32_e32 v87, v0
	v_mov_b32_e32 v88, v0
	v_mov_b32_e32 v89, v0
	v_mov_b32_e32 v90, v0
	v_mov_b32_e32 v91, v0
	v_mov_b32_e32 v92, v0
	v_mov_b32_e32 v93, v0
	v_mov_b32_e32 v94, v0
	v_mov_b32_e32 v95, v0
	v_mov_b32_e32 v32, v0
	v_mov_b32_e32 v33, v0
	v_mov_b32_e32 v34, v0
	v_mov_b32_e32 v35, v0
	v_mov_b32_e32 v36, v0
	v_mov_b32_e32 v37, v0
	v_mov_b32_e32 v38, v0
	v_mov_b32_e32 v39, v0
	v_mov_b32_e32 v40, v0
	v_mov_b32_e32 v41, v0
	v_mov_b32_e32 v42, v0
	v_mov_b32_e32 v43, v0
	v_mov_b32_e32 v44, v0
	v_mov_b32_e32 v45, v0
	v_mov_b32_e32 v46, v0
	v_mov_b32_e32 v47, v0
	v_mov_b32_e32 v48, v0
	v_mov_b32_e32 v49, v0
	v_mov_b32_e32 v50, v0
	v_mov_b32_e32 v51, v0
	v_mov_b32_e32 v56, v0
	v_mov_b32_e32 v57, v0
	v_mov_b32_e32 v58, v0
	v_mov_b32_e32 v59, v0
	v_mov_b32_e32 v64, v0
	v_mov_b32_e32 v65, v0
	v_mov_b32_e32 v66, v0
	v_mov_b32_e32 v67, v0
	v_mov_b32_e32 v68, v0
	v_mov_b32_e32 v69, v0
	v_mov_b32_e32 v70, v0
	v_mov_b32_e32 v71, v0
	v_mov_b32_e32 v96, v0
	v_mov_b32_e32 v97, v0
	v_mov_b32_e32 v98, v0
	v_mov_b32_e32 v99, v0
	v_mov_b32_e32 v100, v0
	v_mov_b32_e32 v101, v0
	v_mov_b32_e32 v102, v0
	v_mov_b32_e32 v103, v0
	v_mov_b32_e32 v104, v0
	v_mov_b32_e32 v105, v0
	v_mov_b32_e32 v106, v0
	v_mov_b32_e32 v107, v0
	v_mov_b32_e32 v108, v0
	v_mov_b32_e32 v109, v0
	v_mov_b32_e32 v110, v0
	v_mov_b32_e32 v111, v0
	v_mov_b32_e32 v112, v0
	v_mov_b32_e32 v113, v0
	v_mov_b32_e32 v114, v0
	v_mov_b32_e32 v115, v0
	v_mov_b32_e32 v116, v0
	v_mov_b32_e32 v117, v0
	v_mov_b32_e32 v118, v0
	v_mov_b32_e32 v119, v0
	v_mov_b32_e32 v120, v0
	v_mov_b32_e32 v121, v0
	v_mov_b32_e32 v122, v0
	v_mov_b32_e32 v123, v0
	v_mov_b32_e32 v124, v0
	v_mov_b32_e32 v125, v0
	v_mov_b32_e32 v126, v0
	v_mov_b32_e32 v127, v0
	s_nop 0
	s_nop 0
	s_nop 0
	s_nop 0
	s_nop 0
	s_nop 0
	s_nop 0
	s_nop 0
	s_nop 0
	s_nop 0
	s_nop 0
	s_nop 0
